# m12 + gate/up epilogue stores paired across adjacent row blocks with v_permlane16_swap into dwordx4 (half the store instructions)
# baseline (speedup 1.0000x reference)
; __device__ __forceinline__ unsigned pk4_fp8(float a, float b, float c, float d) { int w = 0; w = __builtin_amdgcn_cvt_pk_fp8_f32(clamp8(a), clamp8(b), w, false); w = __builtin_amdgcn_cvt_pk_fp8_f32(clamp8(c), clamp8(d), w, true); return (unsigned)w; }
; __device__ __forceinline__ float silu_mul(float g, float u) { return g * __builtin_amdgcn_rcpf(1.0f + __builtin_amdgcn_exp2f(-g * LOG2E)) * u; }
;     __device__ __forceinline__ void operator()(const f32x4 (&acc)[2][2][4][2], const Unit& u, int wr, int wc, int fr, int fq, const unsigned long long (&pf)[8]) const {
;         const int row0 = u.pm * BM + wr * 64 + fr, col0 = u.pn * HALF + wc * 32 + 8 * fq;
; #pragma unroll
;         for (int ai = 0; ai < 2; ++ai)
; #pragma unroll
;             for (int m = 0; m < 4; ++m) { const int row = row0 + ai * HALF + m * 16; const float rs = rsqrtf((float)pf[ai * 4 + m] * (1.0f / (SSQ_SCALE * 1024.0f)) + EPS) * wsc;
;                 const f32x4 g0 = acc[ai][0][m][0] * rs, g1 = acc[ai][0][m][1] * rs, u0 = acc[ai][1][m][0] * rs, u1 = acc[ai][1][m][1] * rs;
;                 u32x2 w; w.x = pk4_fp8(silu_mul(g0[0], u0[0]) * HFF8_SCALE, silu_mul(g0[1], u0[1]) * HFF8_SCALE, silu_mul(g0[2], u0[2]) * HFF8_SCALE, silu_mul(g0[3], u0[3]) * HFF8_SCALE);
;                 w.y = pk4_fp8(silu_mul(g1[0], u1[0]) * HFF8_SCALE, silu_mul(g1[1], u1[1]) * HFF8_SCALE, silu_mul(g1[2], u1[2]) * HFF8_SCALE, silu_mul(g1[3], u1[3]) * HFF8_SCALE);
;                 *(u32x2*)(O + (size_t)row * FF + col0) = w; }
.LBB0_246:
	s_nop 15
	s_nop 7
	s_waitcnt vmcnt(0)
	v_lshl_or_b32 v0, s33, 7, v220
	v_mov_b32_e32 v4, 0x358637bd
	v_ashrrev_i32_e32 v1, 31, v0
	v_mov_b64_e32 v[2:3], s[48:49]
	v_and_b32_e32 v5, 8, v220
	v_mul_u32_u24_e32 v5, 0x15ff, v5
	v_add_u32_e32 v0, v0, v5
	v_mov_b32_e32 v6, 1.0
	v_mov_b32_e32 v7, 1.0
	v_ffbh_u32_e32 v8, v183
	v_ffbh_u32_e32 v12, v181
	v_min_u32_e32 v10, 32, v8
	v_min_u32_e32 v14, 32, v12
	v_lshlrev_b64 v[8:9], v10, v[182:183]
	v_lshlrev_b64 v[12:13], v14, v[180:181]
	v_min_u32_e32 v8, 1, v8
	v_min_u32_e32 v12, 1, v12
	v_or_b32_e32 v8, v9, v8
	v_or_b32_e32 v12, v13, v12
	v_cvt_f32_u32_e32 v8, v8
	v_cvt_f32_u32_e32 v12, v12
	v_sub_u32_e32 v9, 32, v10
	v_sub_u32_e32 v13, 32, v14
	v_ldexp_f32 v8, v8, v9
	v_ldexp_f32 v12, v12, v13
	v_fma_f32 v8, v8, s80, v4
	v_fma_f32 v12, v12, s80, v4
	v_mul_f32_e32 v9, 0x4b800000, v8
	v_mul_f32_e32 v13, 0x4b800000, v12
	v_cmp_gt_f32_e32 vcc, s92, v8
	v_cmp_gt_f32_e64 s[12:13], s92, v12
	s_nop 0
	v_cndmask_b32_e32 v8, v8, v9, vcc
	v_cndmask_b32_e64 v12, v12, v13, s[12:13]
	v_rsq_f32_e32 v8, v8
	v_rsq_f32_e32 v12, v12
	v_mul_f32_e32 v9, 0x45800000, v8
	v_mul_f32_e32 v13, 0x45800000, v12
	v_cndmask_b32_e32 v8, v8, v9, vcc
	v_cndmask_b32_e64 v12, v12, v13, s[12:13]
	v_mul_f32_e32 v8, 0x3c800000, v8
	v_mul_f32_e32 v12, 0x3c800000, v12
	v_mul_f32_e32 v194, 0xbfb8aa3b, v8
	v_mul_f32_e32 v196, 0xbfb8aa3b, v12
	v_mul_f32_e32 v9, v8, v8
	v_mul_f32_e32 v13, v12, v12
	v_mul_f32_e32 v195, 0x41000000, v9
	v_mul_f32_e32 v197, 0x41000000, v13
	v_ffbh_u32_e32 v8, v185
	v_ffbh_u32_e32 v12, v179
	v_min_u32_e32 v10, 32, v8
	v_min_u32_e32 v14, 32, v12
	v_lshlrev_b64 v[8:9], v10, v[184:185]
	v_lshlrev_b64 v[12:13], v14, v[178:179]
	v_min_u32_e32 v8, 1, v8
	v_min_u32_e32 v12, 1, v12
	v_or_b32_e32 v8, v9, v8
	v_or_b32_e32 v12, v13, v12
	v_cvt_f32_u32_e32 v8, v8
	v_cvt_f32_u32_e32 v12, v12
	v_sub_u32_e32 v9, 32, v10
	v_sub_u32_e32 v13, 32, v14
	v_ldexp_f32 v8, v8, v9
	v_ldexp_f32 v12, v12, v13
	v_fma_f32 v8, v8, s80, v4
	v_fma_f32 v12, v12, s80, v4
	v_mul_f32_e32 v9, 0x4b800000, v8
	v_mul_f32_e32 v13, 0x4b800000, v12
	v_cmp_gt_f32_e32 vcc, s92, v8
	v_cmp_gt_f32_e64 s[12:13], s92, v12
	s_nop 0
	v_cndmask_b32_e32 v8, v8, v9, vcc
	v_cndmask_b32_e64 v12, v12, v13, s[12:13]
	v_rsq_f32_e32 v8, v8
	v_rsq_f32_e32 v12, v12
	v_mul_f32_e32 v9, 0x45800000, v8
	v_mul_f32_e32 v13, 0x45800000, v12
	v_cndmask_b32_e32 v8, v8, v9, vcc
	v_cndmask_b32_e64 v12, v12, v13, s[12:13]
	v_mul_f32_e32 v8, 0x3c800000, v8
	v_mul_f32_e32 v12, 0x3c800000, v12
	v_mul_f32_e32 v198, 0xbfb8aa3b, v8
	v_mul_f32_e32 v200, 0xbfb8aa3b, v12
	v_mul_f32_e32 v9, v8, v8
	v_mul_f32_e32 v13, v12, v12
	v_mul_f32_e32 v199, 0x41000000, v9
	v_mul_f32_e32 v201, 0x41000000, v13
	v_ffbh_u32_e32 v8, v187
	v_ffbh_u32_e32 v12, v177
	v_min_u32_e32 v10, 32, v8
	v_min_u32_e32 v14, 32, v12
	v_lshlrev_b64 v[8:9], v10, v[186:187]
	v_lshlrev_b64 v[12:13], v14, v[176:177]
	v_min_u32_e32 v8, 1, v8
	v_min_u32_e32 v12, 1, v12
	v_or_b32_e32 v8, v9, v8
	v_or_b32_e32 v12, v13, v12
	v_cvt_f32_u32_e32 v8, v8
	v_cvt_f32_u32_e32 v12, v12
	v_sub_u32_e32 v9, 32, v10
	v_sub_u32_e32 v13, 32, v14
	v_ldexp_f32 v8, v8, v9
	v_ldexp_f32 v12, v12, v13
	v_fma_f32 v8, v8, s80, v4
	v_fma_f32 v12, v12, s80, v4
	v_mul_f32_e32 v9, 0x4b800000, v8
	v_mul_f32_e32 v13, 0x4b800000, v12
	v_cmp_gt_f32_e32 vcc, s92, v8
	v_cmp_gt_f32_e64 s[12:13], s92, v12
	s_nop 0
	v_cndmask_b32_e32 v8, v8, v9, vcc
	v_cndmask_b32_e64 v12, v12, v13, s[12:13]
	v_rsq_f32_e32 v8, v8
	v_rsq_f32_e32 v12, v12
	v_mul_f32_e32 v9, 0x45800000, v8
	v_mul_f32_e32 v13, 0x45800000, v12
	v_cndmask_b32_e32 v8, v8, v9, vcc
	v_cndmask_b32_e64 v12, v12, v13, s[12:13]
	v_mul_f32_e32 v8, 0x3c800000, v8
	v_mul_f32_e32 v12, 0x3c800000, v12
	v_mul_f32_e32 v246, 0xbfb8aa3b, v8
	v_mul_f32_e32 v248, 0xbfb8aa3b, v12
	v_mul_f32_e32 v9, v8, v8
	v_mul_f32_e32 v13, v12, v12
	v_mul_f32_e32 v247, 0x41000000, v9
	v_mul_f32_e32 v249, 0x41000000, v13
	v_ffbh_u32_e32 v8, v189
	v_ffbh_u32_e32 v12, v175
	v_min_u32_e32 v10, 32, v8
	v_min_u32_e32 v14, 32, v12
	v_lshlrev_b64 v[8:9], v10, v[188:189]
	v_lshlrev_b64 v[12:13], v14, v[174:175]
	v_min_u32_e32 v8, 1, v8
	v_min_u32_e32 v12, 1, v12
	v_or_b32_e32 v8, v9, v8
	v_or_b32_e32 v12, v13, v12
	v_cvt_f32_u32_e32 v8, v8
	v_cvt_f32_u32_e32 v12, v12
	v_sub_u32_e32 v9, 32, v10
	v_sub_u32_e32 v13, 32, v14
	v_ldexp_f32 v8, v8, v9
	v_ldexp_f32 v12, v12, v13
	v_fma_f32 v8, v8, s80, v4
	v_fma_f32 v12, v12, s80, v4
	v_mul_f32_e32 v9, 0x4b800000, v8
	v_mul_f32_e32 v13, 0x4b800000, v12
	v_cmp_gt_f32_e32 vcc, s92, v8
	v_cmp_gt_f32_e64 s[12:13], s92, v12
	s_nop 0
	v_cndmask_b32_e32 v8, v8, v9, vcc
	v_cndmask_b32_e64 v12, v12, v13, s[12:13]
	v_rsq_f32_e32 v8, v8
	v_rsq_f32_e32 v12, v12
	v_mul_f32_e32 v9, 0x45800000, v8
	v_mul_f32_e32 v13, 0x45800000, v12
	v_cndmask_b32_e32 v8, v8, v9, vcc
	v_cndmask_b32_e64 v12, v12, v13, s[12:13]
	v_mul_f32_e32 v8, 0x3c800000, v8
	v_mul_f32_e32 v12, 0x3c800000, v12
	v_mul_f32_e32 v250, 0xbfb8aa3b, v8
	v_mul_f32_e32 v252, 0xbfb8aa3b, v12
	v_mul_f32_e32 v9, v8, v8
	v_mul_f32_e32 v13, v12, v12
	v_mul_f32_e32 v251, 0x41000000, v9
	v_mul_f32_e32 v253, 0x41000000, v13
	v_pk_mul_f32 v[222:223], v[156:157], v[194:195] op_sel_hi:[1,0]
	v_pk_mul_f32 v[224:225], v[158:159], v[194:195] op_sel_hi:[1,0]
	v_pk_mul_f32 v[226:227], v[152:153], v[194:195] op_sel_hi:[1,0]
	v_pk_mul_f32 v[228:229], v[154:155], v[194:195] op_sel_hi:[1,0]
	v_mad_i64_i32 v[16:17], vcc, v190, s93, v[2:3]
	v_exp_f32_e32 v222, v222
	v_exp_f32_e32 v223, v223
	v_exp_f32_e32 v224, v224
	v_exp_f32_e32 v225, v225
	v_exp_f32_e32 v226, v226
	v_exp_f32_e32 v227, v227
	v_exp_f32_e32 v228, v228
	v_exp_f32_e32 v229, v229
	v_pk_mul_f32 v[238:239], v[156:157], v[148:149]
; __device__ __forceinline__ unsigned pk4_fp8(float a, float b, float c, float d) { int w = 0; w = __builtin_amdgcn_cvt_pk_fp8_f32(clamp8(a), clamp8(b), w, false); w = __builtin_amdgcn_cvt_pk_fp8_f32(clamp8(c), clamp8(d), w, true); return (unsigned)w; }
; __device__ __forceinline__ float silu_mul(float g, float u) { return g * __builtin_amdgcn_rcpf(1.0f + __builtin_amdgcn_exp2f(-g * LOG2E)) * u; }
;     __device__ __forceinline__ void operator()(const f32x4 (&acc)[2][2][4][2], const Unit& u, int wr, int wc, int fr, int fq, const unsigned long long (&pf)[8]) const {
;     ...
;             for (int m = 0; m < 4; ++m) { const int row = row0 + ai * HALF + m * 16; const float rs = rsqrtf((float)pf[ai * 4 + m] * (1.0f / (SSQ_SCALE * 1024.0f)) + EPS) * wsc;
;                 const f32x4 g0 = acc[ai][0][m][0] * rs, g1 = acc[ai][0][m][1] * rs, u0 = acc[ai][1][m][0] * rs, u1 = acc[ai][1][m][1] * rs;
;                 u32x2 w; w.x = pk4_fp8(silu_mul(g0[0], u0[0]) * HFF8_SCALE, silu_mul(g0[1], u0[1]) * HFF8_SCALE, silu_mul(g0[2], u0[2]) * HFF8_SCALE, silu_mul(g0[3], u0[3]) * HFF8_SCALE);
;                 w.y = pk4_fp8(silu_mul(g1[0], u1[0]) * HFF8_SCALE, silu_mul(g1[1], u1[1]) * HFF8_SCALE, silu_mul(g1[2], u1[2]) * HFF8_SCALE, silu_mul(g1[3], u1[3]) * HFF8_SCALE);
;                 *(u32x2*)(O + (size_t)row * FF + col0) = w; }
	v_pk_mul_f32 v[240:241], v[158:159], v[150:151]
	v_pk_mul_f32 v[242:243], v[152:153], v[144:145]
	v_pk_mul_f32 v[244:245], v[154:155], v[146:147]
	v_pk_add_f32 v[230:231], v[222:223], v[6:7]
	v_pk_add_f32 v[232:233], v[224:225], v[6:7]
	v_pk_add_f32 v[234:235], v[226:227], v[6:7]
	v_pk_add_f32 v[236:237], v[228:229], v[6:7]
	v_lshl_add_u64 v[16:17], v[16:17], 0, v[0:1]
	v_rcp_f32_e32 v230, v230
	v_rcp_f32_e32 v231, v231
	v_rcp_f32_e32 v232, v232
	v_rcp_f32_e32 v233, v233
	v_rcp_f32_e32 v234, v234
	v_rcp_f32_e32 v235, v235
	v_rcp_f32_e32 v236, v236
	v_rcp_f32_e32 v237, v237
	v_pk_mul_f32 v[238:239], v[238:239], v[194:195] op_sel:[0,1] op_sel_hi:[1,1]
	v_pk_mul_f32 v[240:241], v[240:241], v[194:195] op_sel:[0,1] op_sel_hi:[1,1]
	v_pk_mul_f32 v[242:243], v[242:243], v[194:195] op_sel:[0,1] op_sel_hi:[1,1]
	v_pk_mul_f32 v[244:245], v[244:245], v[194:195] op_sel:[0,1] op_sel_hi:[1,1]
	v_pk_mul_f32 v[238:239], v[238:239], v[230:231]
	v_pk_mul_f32 v[240:241], v[240:241], v[232:233]
	v_pk_mul_f32 v[242:243], v[242:243], v[234:235]
	v_pk_mul_f32 v[244:245], v[244:245], v[236:237]
	v_med3_f32 v238, v238, s38, v210
	v_med3_f32 v239, v239, s38, v210
	v_med3_f32 v240, v240, s38, v210
	v_med3_f32 v241, v241, s38, v210
	v_med3_f32 v242, v242, s38, v210
	v_med3_f32 v243, v243, s38, v210
	v_med3_f32 v244, v244, s38, v210
	v_med3_f32 v245, v245, s38, v210
	v_cvt_pk_fp8_f32 v20, v238, v239
	v_cvt_pk_fp8_f32 v21, v242, v243
	v_cvt_pk_fp8_f32 v20, v240, v241 op_sel:[0,0,1]
	v_cvt_pk_fp8_f32 v21, v244, v245 op_sel:[0,0,1]
	v_add_u32_e32 v24, 0x10, v190
	v_pk_mul_f32 v[222:223], v[140:141], v[196:197] op_sel_hi:[1,0]
	v_pk_mul_f32 v[224:225], v[142:143], v[196:197] op_sel_hi:[1,0]
	v_pk_mul_f32 v[226:227], v[136:137], v[196:197] op_sel_hi:[1,0]
	v_pk_mul_f32 v[228:229], v[138:139], v[196:197] op_sel_hi:[1,0]
	v_exp_f32_e32 v222, v222
	v_exp_f32_e32 v223, v223
	v_exp_f32_e32 v224, v224
	v_exp_f32_e32 v225, v225
	v_exp_f32_e32 v226, v226
	v_exp_f32_e32 v227, v227
	v_exp_f32_e32 v228, v228
	v_exp_f32_e32 v229, v229
	v_pk_mul_f32 v[238:239], v[140:141], v[132:133]
	v_pk_mul_f32 v[240:241], v[142:143], v[134:135]
	v_pk_mul_f32 v[242:243], v[136:137], v[128:129]
	v_pk_mul_f32 v[244:245], v[138:139], v[130:131]
	v_pk_add_f32 v[230:231], v[222:223], v[6:7]
	v_pk_add_f32 v[232:233], v[224:225], v[6:7]
	v_pk_add_f32 v[234:235], v[226:227], v[6:7]
	v_pk_add_f32 v[236:237], v[228:229], v[6:7]
	v_rcp_f32_e32 v230, v230
	v_rcp_f32_e32 v231, v231
	v_rcp_f32_e32 v232, v232
	v_rcp_f32_e32 v233, v233
	v_rcp_f32_e32 v234, v234
	v_rcp_f32_e32 v235, v235
	v_rcp_f32_e32 v236, v236
	v_rcp_f32_e32 v237, v237
	v_pk_mul_f32 v[238:239], v[238:239], v[196:197] op_sel:[0,1] op_sel_hi:[1,1]
	v_pk_mul_f32 v[240:241], v[240:241], v[196:197] op_sel:[0,1] op_sel_hi:[1,1]
	v_pk_mul_f32 v[242:243], v[242:243], v[196:197] op_sel:[0,1] op_sel_hi:[1,1]
	v_pk_mul_f32 v[244:245], v[244:245], v[196:197] op_sel:[0,1] op_sel_hi:[1,1]
	v_pk_mul_f32 v[238:239], v[238:239], v[230:231]
	v_pk_mul_f32 v[240:241], v[240:241], v[232:233]
	v_pk_mul_f32 v[242:243], v[242:243], v[234:235]
	v_pk_mul_f32 v[244:245], v[244:245], v[236:237]
	v_med3_f32 v238, v238, s38, v210
	v_med3_f32 v239, v239, s38, v210
	v_med3_f32 v240, v240, s38, v210
	v_med3_f32 v241, v241, s38, v210
	v_med3_f32 v242, v242, s38, v210
	v_med3_f32 v243, v243, s38, v210
	v_med3_f32 v244, v244, s38, v210
	v_med3_f32 v245, v245, s38, v210
	v_cvt_pk_fp8_f32 v22, v238, v239
	v_cvt_pk_fp8_f32 v23, v242, v243
	v_cvt_pk_fp8_f32 v22, v240, v241 op_sel:[0,0,1]
	v_cvt_pk_fp8_f32 v23, v244, v245 op_sel:[0,0,1]
	s_nop 1
	v_permlane16_swap_b32_e32 v20, v22
	v_permlane16_swap_b32_e32 v21, v23
	s_nop 0
	global_store_dwordx4 v[16:17], v[20:23], off
	v_add_u32_e32 v24, 0x20, v190
	v_pk_mul_f32 v[222:223], v[124:125], v[198:199] op_sel_hi:[1,0]
	v_pk_mul_f32 v[224:225], v[126:127], v[198:199] op_sel_hi:[1,0]
	v_pk_mul_f32 v[226:227], v[120:121], v[198:199] op_sel_hi:[1,0]
	v_pk_mul_f32 v[228:229], v[122:123], v[198:199] op_sel_hi:[1,0]
	v_mad_i64_i32 v[16:17], vcc, v24, s93, v[2:3]
	v_exp_f32_e32 v222, v222
	v_exp_f32_e32 v223, v223
	v_exp_f32_e32 v224, v224
	v_exp_f32_e32 v225, v225
	v_exp_f32_e32 v226, v226
	v_exp_f32_e32 v227, v227
	v_exp_f32_e32 v228, v228
	v_exp_f32_e32 v229, v229
	v_pk_mul_f32 v[238:239], v[124:125], v[116:117]
	v_pk_mul_f32 v[240:241], v[126:127], v[118:119]
	v_pk_mul_f32 v[242:243], v[120:121], v[112:113]
	v_pk_mul_f32 v[244:245], v[122:123], v[114:115]
	v_pk_add_f32 v[230:231], v[222:223], v[6:7]
	v_pk_add_f32 v[232:233], v[224:225], v[6:7]
	v_pk_add_f32 v[234:235], v[226:227], v[6:7]
	v_pk_add_f32 v[236:237], v[228:229], v[6:7]
	v_lshl_add_u64 v[16:17], v[16:17], 0, v[0:1]
	v_rcp_f32_e32 v230, v230
	v_rcp_f32_e32 v231, v231
	v_rcp_f32_e32 v232, v232
	v_rcp_f32_e32 v233, v233
	v_rcp_f32_e32 v234, v234
	v_rcp_f32_e32 v235, v235
	v_rcp_f32_e32 v236, v236
	v_rcp_f32_e32 v237, v237
	v_pk_mul_f32 v[238:239], v[238:239], v[198:199] op_sel:[0,1] op_sel_hi:[1,1]
	v_pk_mul_f32 v[240:241], v[240:241], v[198:199] op_sel:[0,1] op_sel_hi:[1,1]
	v_pk_mul_f32 v[242:243], v[242:243], v[198:199] op_sel:[0,1] op_sel_hi:[1,1]
	v_pk_mul_f32 v[244:245], v[244:245], v[198:199] op_sel:[0,1] op_sel_hi:[1,1]
	v_pk_mul_f32 v[238:239], v[238:239], v[230:231]
	v_pk_mul_f32 v[240:241], v[240:241], v[232:233]
	v_pk_mul_f32 v[242:243], v[242:243], v[234:235]
	v_pk_mul_f32 v[244:245], v[244:245], v[236:237]
	v_med3_f32 v238, v238, s38, v210
	v_med3_f32 v239, v239, s38, v210
	v_med3_f32 v240, v240, s38, v210
	v_med3_f32 v241, v241, s38, v210
	v_med3_f32 v242, v242, s38, v210
	v_med3_f32 v243, v243, s38, v210
	v_med3_f32 v244, v244, s38, v210
	v_med3_f32 v245, v245, s38, v210
; __device__ __forceinline__ unsigned pk4_fp8(float a, float b, float c, float d) { int w = 0; w = __builtin_amdgcn_cvt_pk_fp8_f32(clamp8(a), clamp8(b), w, false); w = __builtin_amdgcn_cvt_pk_fp8_f32(clamp8(c), clamp8(d), w, true); return (unsigned)w; }
; __device__ __forceinline__ float silu_mul(float g, float u) { return g * __builtin_amdgcn_rcpf(1.0f + __builtin_amdgcn_exp2f(-g * LOG2E)) * u; }
;     __device__ __forceinline__ void operator()(const f32x4 (&acc)[2][2][4][2], const Unit& u, int wr, int wc, int fr, int fq, const unsigned long long (&pf)[8]) const {
;     ...
;             for (int m = 0; m < 4; ++m) { const int row = row0 + ai * HALF + m * 16; const float rs = rsqrtf((float)pf[ai * 4 + m] * (1.0f / (SSQ_SCALE * 1024.0f)) + EPS) * wsc;
;                 const f32x4 g0 = acc[ai][0][m][0] * rs, g1 = acc[ai][0][m][1] * rs, u0 = acc[ai][1][m][0] * rs, u1 = acc[ai][1][m][1] * rs;
;                 u32x2 w; w.x = pk4_fp8(silu_mul(g0[0], u0[0]) * HFF8_SCALE, silu_mul(g0[1], u0[1]) * HFF8_SCALE, silu_mul(g0[2], u0[2]) * HFF8_SCALE, silu_mul(g0[3], u0[3]) * HFF8_SCALE);
;                 w.y = pk4_fp8(silu_mul(g1[0], u1[0]) * HFF8_SCALE, silu_mul(g1[1], u1[1]) * HFF8_SCALE, silu_mul(g1[2], u1[2]) * HFF8_SCALE, silu_mul(g1[3], u1[3]) * HFF8_SCALE);
;                 *(u32x2*)(O + (size_t)row * FF + col0) = w; }
	v_cvt_pk_fp8_f32 v20, v238, v239
	v_cvt_pk_fp8_f32 v21, v242, v243
	v_cvt_pk_fp8_f32 v20, v240, v241 op_sel:[0,0,1]
	v_cvt_pk_fp8_f32 v21, v244, v245 op_sel:[0,0,1]
	v_add_u32_e32 v24, 0x30, v190
	v_pk_mul_f32 v[222:223], v[108:109], v[200:201] op_sel_hi:[1,0]
	v_pk_mul_f32 v[224:225], v[110:111], v[200:201] op_sel_hi:[1,0]
	v_pk_mul_f32 v[226:227], v[104:105], v[200:201] op_sel_hi:[1,0]
	v_pk_mul_f32 v[228:229], v[106:107], v[200:201] op_sel_hi:[1,0]
	v_exp_f32_e32 v222, v222
	v_exp_f32_e32 v223, v223
	v_exp_f32_e32 v224, v224
	v_exp_f32_e32 v225, v225
	v_exp_f32_e32 v226, v226
	v_exp_f32_e32 v227, v227
	v_exp_f32_e32 v228, v228
	v_exp_f32_e32 v229, v229
	v_pk_mul_f32 v[238:239], v[108:109], v[100:101]
	v_pk_mul_f32 v[240:241], v[110:111], v[102:103]
	v_pk_mul_f32 v[242:243], v[104:105], v[96:97]
	v_pk_mul_f32 v[244:245], v[106:107], v[98:99]
	v_pk_add_f32 v[230:231], v[222:223], v[6:7]
	v_pk_add_f32 v[232:233], v[224:225], v[6:7]
	v_pk_add_f32 v[234:235], v[226:227], v[6:7]
	v_pk_add_f32 v[236:237], v[228:229], v[6:7]
	v_rcp_f32_e32 v230, v230
	v_rcp_f32_e32 v231, v231
	v_rcp_f32_e32 v232, v232
	v_rcp_f32_e32 v233, v233
	v_rcp_f32_e32 v234, v234
	v_rcp_f32_e32 v235, v235
	v_rcp_f32_e32 v236, v236
	v_rcp_f32_e32 v237, v237
	v_pk_mul_f32 v[238:239], v[238:239], v[200:201] op_sel:[0,1] op_sel_hi:[1,1]
	v_pk_mul_f32 v[240:241], v[240:241], v[200:201] op_sel:[0,1] op_sel_hi:[1,1]
	v_pk_mul_f32 v[242:243], v[242:243], v[200:201] op_sel:[0,1] op_sel_hi:[1,1]
	v_pk_mul_f32 v[244:245], v[244:245], v[200:201] op_sel:[0,1] op_sel_hi:[1,1]
	v_pk_mul_f32 v[238:239], v[238:239], v[230:231]
	v_pk_mul_f32 v[240:241], v[240:241], v[232:233]
	v_pk_mul_f32 v[242:243], v[242:243], v[234:235]
	v_pk_mul_f32 v[244:245], v[244:245], v[236:237]
	v_med3_f32 v238, v238, s38, v210
	v_med3_f32 v239, v239, s38, v210
	v_med3_f32 v240, v240, s38, v210
	v_med3_f32 v241, v241, s38, v210
	v_med3_f32 v242, v242, s38, v210
	v_med3_f32 v243, v243, s38, v210
	v_med3_f32 v244, v244, s38, v210
	v_med3_f32 v245, v245, s38, v210
	v_cvt_pk_fp8_f32 v22, v238, v239
	v_cvt_pk_fp8_f32 v23, v242, v243
	v_cvt_pk_fp8_f32 v22, v240, v241 op_sel:[0,0,1]
	v_cvt_pk_fp8_f32 v23, v244, v245 op_sel:[0,0,1]
	s_nop 1
	v_permlane16_swap_b32_e32 v20, v22
	v_permlane16_swap_b32_e32 v21, v23
	s_nop 0
	global_store_dwordx4 v[16:17], v[20:23], off
	v_add_u32_e32 v24, 0x80, v190
	v_pk_mul_f32 v[222:223], v[92:93], v[246:247] op_sel_hi:[1,0]
	v_pk_mul_f32 v[224:225], v[94:95], v[246:247] op_sel_hi:[1,0]
	v_pk_mul_f32 v[226:227], v[88:89], v[246:247] op_sel_hi:[1,0]
	v_pk_mul_f32 v[228:229], v[90:91], v[246:247] op_sel_hi:[1,0]
	v_mad_i64_i32 v[16:17], vcc, v24, s93, v[2:3]
	v_exp_f32_e32 v222, v222
	v_exp_f32_e32 v223, v223
	v_exp_f32_e32 v224, v224
	v_exp_f32_e32 v225, v225
	v_exp_f32_e32 v226, v226
	v_exp_f32_e32 v227, v227
	v_exp_f32_e32 v228, v228
	v_exp_f32_e32 v229, v229
	v_pk_mul_f32 v[238:239], v[92:93], v[84:85]
	v_pk_mul_f32 v[240:241], v[94:95], v[86:87]
	v_pk_mul_f32 v[242:243], v[88:89], v[80:81]
	v_pk_mul_f32 v[244:245], v[90:91], v[82:83]
	v_pk_add_f32 v[230:231], v[222:223], v[6:7]
	v_pk_add_f32 v[232:233], v[224:225], v[6:7]
	v_pk_add_f32 v[234:235], v[226:227], v[6:7]
	v_pk_add_f32 v[236:237], v[228:229], v[6:7]
	v_lshl_add_u64 v[16:17], v[16:17], 0, v[0:1]
	v_rcp_f32_e32 v230, v230
	v_rcp_f32_e32 v231, v231
	v_rcp_f32_e32 v232, v232
	v_rcp_f32_e32 v233, v233
	v_rcp_f32_e32 v234, v234
	v_rcp_f32_e32 v235, v235
	v_rcp_f32_e32 v236, v236
	v_rcp_f32_e32 v237, v237
	v_pk_mul_f32 v[238:239], v[238:239], v[246:247] op_sel:[0,1] op_sel_hi:[1,1]
	v_pk_mul_f32 v[240:241], v[240:241], v[246:247] op_sel:[0,1] op_sel_hi:[1,1]
	v_pk_mul_f32 v[242:243], v[242:243], v[246:247] op_sel:[0,1] op_sel_hi:[1,1]
	v_pk_mul_f32 v[244:245], v[244:245], v[246:247] op_sel:[0,1] op_sel_hi:[1,1]
	v_pk_mul_f32 v[238:239], v[238:239], v[230:231]
	v_pk_mul_f32 v[240:241], v[240:241], v[232:233]
	v_pk_mul_f32 v[242:243], v[242:243], v[234:235]
	v_pk_mul_f32 v[244:245], v[244:245], v[236:237]
	v_med3_f32 v238, v238, s38, v210
	v_med3_f32 v239, v239, s38, v210
	v_med3_f32 v240, v240, s38, v210
	v_med3_f32 v241, v241, s38, v210
	v_med3_f32 v242, v242, s38, v210
	v_med3_f32 v243, v243, s38, v210
	v_med3_f32 v244, v244, s38, v210
	v_med3_f32 v245, v245, s38, v210
	v_cvt_pk_fp8_f32 v20, v238, v239
	v_cvt_pk_fp8_f32 v21, v242, v243
	v_cvt_pk_fp8_f32 v20, v240, v241 op_sel:[0,0,1]
	v_cvt_pk_fp8_f32 v21, v244, v245 op_sel:[0,0,1]
	v_add_u32_e32 v24, 0x90, v190
	v_pk_mul_f32 v[222:223], v[76:77], v[248:249] op_sel_hi:[1,0]
	v_pk_mul_f32 v[224:225], v[78:79], v[248:249] op_sel_hi:[1,0]
	v_pk_mul_f32 v[226:227], v[72:73], v[248:249] op_sel_hi:[1,0]
	v_pk_mul_f32 v[228:229], v[74:75], v[248:249] op_sel_hi:[1,0]
	v_exp_f32_e32 v222, v222
	v_exp_f32_e32 v223, v223
	v_exp_f32_e32 v224, v224
	v_exp_f32_e32 v225, v225
	v_exp_f32_e32 v226, v226
	v_exp_f32_e32 v227, v227
	v_exp_f32_e32 v228, v228
	v_exp_f32_e32 v229, v229
	v_pk_mul_f32 v[238:239], v[76:77], v[68:69]
	v_pk_mul_f32 v[240:241], v[78:79], v[70:71]
	v_pk_mul_f32 v[242:243], v[72:73], v[64:65]
	v_pk_mul_f32 v[244:245], v[74:75], v[66:67]
	v_pk_add_f32 v[230:231], v[222:223], v[6:7]
	v_pk_add_f32 v[232:233], v[224:225], v[6:7]
	v_pk_add_f32 v[234:235], v[226:227], v[6:7]
	v_pk_add_f32 v[236:237], v[228:229], v[6:7]
	v_rcp_f32_e32 v230, v230
	v_rcp_f32_e32 v231, v231
	v_rcp_f32_e32 v232, v232
	v_rcp_f32_e32 v233, v233
	v_rcp_f32_e32 v234, v234
	v_rcp_f32_e32 v235, v235
	v_rcp_f32_e32 v236, v236
	v_rcp_f32_e32 v237, v237
; __device__ __forceinline__ unsigned pk4_fp8(float a, float b, float c, float d) { int w = 0; w = __builtin_amdgcn_cvt_pk_fp8_f32(clamp8(a), clamp8(b), w, false); w = __builtin_amdgcn_cvt_pk_fp8_f32(clamp8(c), clamp8(d), w, true); return (unsigned)w; }
; __device__ __forceinline__ float silu_mul(float g, float u) { return g * __builtin_amdgcn_rcpf(1.0f + __builtin_amdgcn_exp2f(-g * LOG2E)) * u; }
;     __device__ __forceinline__ void operator()(const f32x4 (&acc)[2][2][4][2], const Unit& u, int wr, int wc, int fr, int fq, const unsigned long long (&pf)[8]) const {
;     ...
;             for (int m = 0; m < 4; ++m) { const int row = row0 + ai * HALF + m * 16; const float rs = rsqrtf((float)pf[ai * 4 + m] * (1.0f / (SSQ_SCALE * 1024.0f)) + EPS) * wsc;
;                 const f32x4 g0 = acc[ai][0][m][0] * rs, g1 = acc[ai][0][m][1] * rs, u0 = acc[ai][1][m][0] * rs, u1 = acc[ai][1][m][1] * rs;
;                 u32x2 w; w.x = pk4_fp8(silu_mul(g0[0], u0[0]) * HFF8_SCALE, silu_mul(g0[1], u0[1]) * HFF8_SCALE, silu_mul(g0[2], u0[2]) * HFF8_SCALE, silu_mul(g0[3], u0[3]) * HFF8_SCALE);
;                 w.y = pk4_fp8(silu_mul(g1[0], u1[0]) * HFF8_SCALE, silu_mul(g1[1], u1[1]) * HFF8_SCALE, silu_mul(g1[2], u1[2]) * HFF8_SCALE, silu_mul(g1[3], u1[3]) * HFF8_SCALE);
;                 *(u32x2*)(O + (size_t)row * FF + col0) = w; }
	v_pk_mul_f32 v[238:239], v[238:239], v[248:249] op_sel:[0,1] op_sel_hi:[1,1]
	v_pk_mul_f32 v[240:241], v[240:241], v[248:249] op_sel:[0,1] op_sel_hi:[1,1]
	v_pk_mul_f32 v[242:243], v[242:243], v[248:249] op_sel:[0,1] op_sel_hi:[1,1]
	v_pk_mul_f32 v[244:245], v[244:245], v[248:249] op_sel:[0,1] op_sel_hi:[1,1]
	v_pk_mul_f32 v[238:239], v[238:239], v[230:231]
	v_pk_mul_f32 v[240:241], v[240:241], v[232:233]
	v_pk_mul_f32 v[242:243], v[242:243], v[234:235]
	v_pk_mul_f32 v[244:245], v[244:245], v[236:237]
	v_med3_f32 v238, v238, s38, v210
	v_med3_f32 v239, v239, s38, v210
	v_med3_f32 v240, v240, s38, v210
	v_med3_f32 v241, v241, s38, v210
	v_med3_f32 v242, v242, s38, v210
	v_med3_f32 v243, v243, s38, v210
	v_med3_f32 v244, v244, s38, v210
	v_med3_f32 v245, v245, s38, v210
	v_cvt_pk_fp8_f32 v22, v238, v239
	v_cvt_pk_fp8_f32 v23, v242, v243
	v_cvt_pk_fp8_f32 v22, v240, v241 op_sel:[0,0,1]
	v_cvt_pk_fp8_f32 v23, v244, v245 op_sel:[0,0,1]
	s_nop 1
	v_permlane16_swap_b32_e32 v20, v22
	v_permlane16_swap_b32_e32 v21, v23
	s_nop 0
	global_store_dwordx4 v[16:17], v[20:23], off
	v_add_u32_e32 v24, 0xa0, v190
	v_pk_mul_f32 v[222:223], v[60:61], v[250:251] op_sel_hi:[1,0]
	v_pk_mul_f32 v[224:225], v[62:63], v[250:251] op_sel_hi:[1,0]
	v_pk_mul_f32 v[226:227], v[56:57], v[250:251] op_sel_hi:[1,0]
	v_pk_mul_f32 v[228:229], v[58:59], v[250:251] op_sel_hi:[1,0]
	v_mad_i64_i32 v[16:17], vcc, v24, s93, v[2:3]
	v_exp_f32_e32 v222, v222
	v_exp_f32_e32 v223, v223
	v_exp_f32_e32 v224, v224
	v_exp_f32_e32 v225, v225
	v_exp_f32_e32 v226, v226
	v_exp_f32_e32 v227, v227
	v_exp_f32_e32 v228, v228
	v_exp_f32_e32 v229, v229
	v_pk_mul_f32 v[238:239], v[60:61], v[52:53]
	v_pk_mul_f32 v[240:241], v[62:63], v[54:55]
	v_pk_mul_f32 v[242:243], v[56:57], v[48:49]
	v_pk_mul_f32 v[244:245], v[58:59], v[50:51]
	v_pk_add_f32 v[230:231], v[222:223], v[6:7]
	v_pk_add_f32 v[232:233], v[224:225], v[6:7]
	v_pk_add_f32 v[234:235], v[226:227], v[6:7]
	v_pk_add_f32 v[236:237], v[228:229], v[6:7]
	v_lshl_add_u64 v[16:17], v[16:17], 0, v[0:1]
	v_rcp_f32_e32 v230, v230
	v_rcp_f32_e32 v231, v231
	v_rcp_f32_e32 v232, v232
	v_rcp_f32_e32 v233, v233
	v_rcp_f32_e32 v234, v234
	v_rcp_f32_e32 v235, v235
	v_rcp_f32_e32 v236, v236
	v_rcp_f32_e32 v237, v237
	v_pk_mul_f32 v[238:239], v[238:239], v[250:251] op_sel:[0,1] op_sel_hi:[1,1]
	v_pk_mul_f32 v[240:241], v[240:241], v[250:251] op_sel:[0,1] op_sel_hi:[1,1]
	v_pk_mul_f32 v[242:243], v[242:243], v[250:251] op_sel:[0,1] op_sel_hi:[1,1]
	v_pk_mul_f32 v[244:245], v[244:245], v[250:251] op_sel:[0,1] op_sel_hi:[1,1]
	v_pk_mul_f32 v[238:239], v[238:239], v[230:231]
	v_pk_mul_f32 v[240:241], v[240:241], v[232:233]
	v_pk_mul_f32 v[242:243], v[242:243], v[234:235]
	v_pk_mul_f32 v[244:245], v[244:245], v[236:237]
	v_med3_f32 v238, v238, s38, v210
	v_med3_f32 v239, v239, s38, v210
	v_med3_f32 v240, v240, s38, v210
	v_med3_f32 v241, v241, s38, v210
	v_med3_f32 v242, v242, s38, v210
	v_med3_f32 v243, v243, s38, v210
	v_med3_f32 v244, v244, s38, v210
	v_med3_f32 v245, v245, s38, v210
	v_cvt_pk_fp8_f32 v20, v238, v239
	v_cvt_pk_fp8_f32 v21, v242, v243
	v_cvt_pk_fp8_f32 v20, v240, v241 op_sel:[0,0,1]
	v_cvt_pk_fp8_f32 v21, v244, v245 op_sel:[0,0,1]
	v_add_u32_e32 v24, 0xb0, v190
	v_pk_mul_f32 v[222:223], v[44:45], v[252:253] op_sel_hi:[1,0]
	v_pk_mul_f32 v[224:225], v[46:47], v[252:253] op_sel_hi:[1,0]
	v_pk_mul_f32 v[226:227], v[40:41], v[252:253] op_sel_hi:[1,0]
	v_pk_mul_f32 v[228:229], v[42:43], v[252:253] op_sel_hi:[1,0]
	v_exp_f32_e32 v222, v222
	v_exp_f32_e32 v223, v223
	v_exp_f32_e32 v224, v224
	v_exp_f32_e32 v225, v225
	v_exp_f32_e32 v226, v226
	v_exp_f32_e32 v227, v227
	v_exp_f32_e32 v228, v228
	v_exp_f32_e32 v229, v229
	v_pk_mul_f32 v[238:239], v[44:45], v[36:37]
	v_pk_mul_f32 v[240:241], v[46:47], v[38:39]
	v_pk_mul_f32 v[242:243], v[40:41], v[32:33]
	v_pk_mul_f32 v[244:245], v[42:43], v[34:35]
	v_pk_add_f32 v[230:231], v[222:223], v[6:7]
	v_pk_add_f32 v[232:233], v[224:225], v[6:7]
	v_pk_add_f32 v[234:235], v[226:227], v[6:7]
	v_pk_add_f32 v[236:237], v[228:229], v[6:7]
	v_rcp_f32_e32 v230, v230
	v_rcp_f32_e32 v231, v231
	v_rcp_f32_e32 v232, v232
	v_rcp_f32_e32 v233, v233
	v_rcp_f32_e32 v234, v234
	v_rcp_f32_e32 v235, v235
	v_rcp_f32_e32 v236, v236
	v_rcp_f32_e32 v237, v237
	v_pk_mul_f32 v[238:239], v[238:239], v[252:253] op_sel:[0,1] op_sel_hi:[1,1]
	v_pk_mul_f32 v[240:241], v[240:241], v[252:253] op_sel:[0,1] op_sel_hi:[1,1]
	v_pk_mul_f32 v[242:243], v[242:243], v[252:253] op_sel:[0,1] op_sel_hi:[1,1]
	v_pk_mul_f32 v[244:245], v[244:245], v[252:253] op_sel:[0,1] op_sel_hi:[1,1]
	v_pk_mul_f32 v[238:239], v[238:239], v[230:231]
	v_pk_mul_f32 v[240:241], v[240:241], v[232:233]
	v_pk_mul_f32 v[242:243], v[242:243], v[234:235]
	v_pk_mul_f32 v[244:245], v[244:245], v[236:237]
	v_med3_f32 v238, v238, s38, v210
	v_med3_f32 v239, v239, s38, v210
	v_med3_f32 v240, v240, s38, v210
	v_med3_f32 v241, v241, s38, v210
	v_med3_f32 v242, v242, s38, v210
	v_med3_f32 v243, v243, s38, v210
	v_med3_f32 v244, v244, s38, v210
	v_med3_f32 v245, v245, s38, v210
	v_cvt_pk_fp8_f32 v22, v238, v239
	v_cvt_pk_fp8_f32 v23, v242, v243
	v_cvt_pk_fp8_f32 v22, v240, v241 op_sel:[0,0,1]
	v_cvt_pk_fp8_f32 v23, v244, v245 op_sel:[0,0,1]
	s_nop 1
	v_permlane16_swap_b32_e32 v20, v22
	v_permlane16_swap_b32_e32 v21, v23
	s_nop 0
	global_store_dwordx4 v[16:17], v[20:23], off
	s_mov_b64 s[12:13], -1
	s_andn2_b64 vcc, exec, s[10:11]
	s_cbranch_vccnz .LBB0_237
	s_andn2_b64 vcc, exec, s[14:15]
	s_cbranch_vccnz .LBB0_236
	s_barrier
	s_branch .LBB0_236
